# adds: relu^2 (Z) epilogue stores marked sc1 (write-through, not retained in L2) so the 128 KB/unit of output does not evict streamed operand tiles
# baseline (speedup 1.0000x reference)
.LBB0_810:
	v_max_f32_e32 v122, v122, v122
	v_lshl_add_u32 v154, s40, 8, v1
	v_max_f32_e32 v122, 0, v122
	v_max_f32_e32 v123, v123, v123
	v_max_f32_e32 v124, v124, v124
	v_lshl_or_b32 v146, s63, 8, v149
	v_ashrrev_i32_e32 v155, 31, v154
	v_mul_f32_e32 v153, v122, v122
	v_max_f32_e32 v122, v127, v127
	v_max_f32_e32 v123, 0, v123
	v_max_f32_e32 v124, 0, v124
	v_ashrrev_i32_e32 v147, 31, v146
	v_lshlrev_b64 v[156:157], 15, v[154:155]
	v_max_f32_e32 v126, v126, v126
	v_max_f32_e32 v122, 0, v122
	v_mul_f32_e32 v127, v123, v123
	v_max_f32_e32 v123, v128, v128
	v_mul_f32_e32 v128, v124, v124
	v_max_f32_e32 v124, v129, v129
	v_max_f32_e32 v125, v125, v125
	v_lshl_add_u64 v[156:157], s[86:87], 0, v[156:157]
	v_lshlrev_b64 v[158:159], 1, v[146:147]
	v_max_f32_e32 v126, 0, v126
	v_mul_f32_e32 v122, v122, v122
	v_max_f32_e32 v123, 0, v123
	v_max_f32_e32 v124, 0, v124
	v_max_f32_e32 v125, 0, v125
	v_max_f32_e32 v114, v114, v114
	v_lshl_add_u64 v[146:147], v[156:157], 0, v[158:159]
	v_mul_f32_e32 v126, v126, v126
	v_mul_f32_e32 v123, v123, v123
	v_mul_f32_e32 v124, v124, v124
	v_mul_f32_e32 v125, v125, v125
	v_cvt_pk_bf16_f32 v122, v126, v122
	v_max_f32_e32 v114, 0, v114
	v_max_f32_e32 v115, v115, v115
	v_max_f32_e32 v116, v116, v116
	v_cvt_pk_bf16_f32 v123, v123, v124
	v_cvt_pk_bf16_f32 v124, v153, v127
	v_cvt_pk_bf16_f32 v125, v128, v125
	global_store_dwordx4 v[146:147], v[122:125], off sc1
	v_max_f32_e32 v115, 0, v115
	v_max_f32_e32 v116, 0, v116
	v_mul_f32_e32 v122, v114, v114
	v_max_f32_e32 v114, v119, v119
	v_max_f32_e32 v118, v118, v118
	v_max_f32_e32 v114, 0, v114
	v_mul_f32_e32 v119, v115, v115
	v_max_f32_e32 v115, v120, v120
	v_mul_f32_e32 v120, v116, v116
	v_max_f32_e32 v116, v121, v121
	v_max_f32_e32 v117, v117, v117
	v_max_f32_e32 v118, 0, v118
	v_mul_f32_e32 v114, v114, v114
	v_max_f32_e32 v115, 0, v115
	v_max_f32_e32 v116, 0, v116
	v_max_f32_e32 v117, 0, v117
	v_mul_f32_e32 v118, v118, v118
	v_mul_f32_e32 v115, v115, v115
	v_mul_f32_e32 v116, v116, v116
	v_mul_f32_e32 v117, v117, v117
	v_cvt_pk_bf16_f32 v114, v118, v114
	v_max_f32_e32 v106, v106, v106
	v_cvt_pk_bf16_f32 v115, v115, v116
	v_cvt_pk_bf16_f32 v116, v122, v119
	v_cvt_pk_bf16_f32 v117, v120, v117
	global_store_dwordx4 v[146:147], v[114:117], off offset:256 sc1
	v_max_f32_e32 v106, 0, v106
	v_max_f32_e32 v107, v107, v107
	v_or_b32_e32 v114, 16, v154
	v_max_f32_e32 v108, v108, v108
	v_ashrrev_i32_e32 v115, 31, v114
	v_mul_f32_e32 v116, v106, v106
	v_max_f32_e32 v106, v111, v111
	v_max_f32_e32 v107, 0, v107
	v_max_f32_e32 v108, 0, v108
	v_lshlrev_b64 v[114:115], 15, v[114:115]
	v_max_f32_e32 v110, v110, v110
	v_max_f32_e32 v106, 0, v106
	v_mul_f32_e32 v111, v107, v107
	v_max_f32_e32 v107, v112, v112
	v_mul_f32_e32 v112, v108, v108
	v_max_f32_e32 v108, v113, v113
	v_max_f32_e32 v109, v109, v109
	v_lshl_add_u64 v[114:115], s[86:87], 0, v[114:115]
	v_max_f32_e32 v110, 0, v110
	v_mul_f32_e32 v106, v106, v106
	v_max_f32_e32 v107, 0, v107
	v_max_f32_e32 v108, 0, v108
	v_max_f32_e32 v109, 0, v109
	v_max_f32_e32 v98, v98, v98
	v_lshl_add_u64 v[114:115], v[114:115], 0, v[158:159]
	v_mul_f32_e32 v110, v110, v110
	v_mul_f32_e32 v107, v107, v107
	v_mul_f32_e32 v108, v108, v108
	v_mul_f32_e32 v109, v109, v109
	v_cvt_pk_bf16_f32 v106, v110, v106
	v_max_f32_e32 v98, 0, v98
	v_max_f32_e32 v99, v99, v99
	v_max_f32_e32 v100, v100, v100
	v_cvt_pk_bf16_f32 v107, v107, v108
	v_cvt_pk_bf16_f32 v108, v116, v111
	v_cvt_pk_bf16_f32 v109, v112, v109
	global_store_dwordx4 v[114:115], v[106:109], off sc1
	v_max_f32_e32 v99, 0, v99
	v_max_f32_e32 v100, 0, v100
	v_mul_f32_e32 v106, v98, v98
	v_max_f32_e32 v98, v103, v103
	v_max_f32_e32 v102, v102, v102
	v_max_f32_e32 v98, 0, v98
	v_mul_f32_e32 v103, v99, v99
	v_max_f32_e32 v99, v104, v104
	v_mul_f32_e32 v104, v100, v100
	v_max_f32_e32 v100, v105, v105
	v_max_f32_e32 v101, v101, v101
	v_max_f32_e32 v102, 0, v102
	v_mul_f32_e32 v98, v98, v98
	v_max_f32_e32 v99, 0, v99
	v_max_f32_e32 v100, 0, v100
	v_max_f32_e32 v101, 0, v101
	v_mul_f32_e32 v102, v102, v102
	v_mul_f32_e32 v99, v99, v99
	v_mul_f32_e32 v100, v100, v100
	v_mul_f32_e32 v101, v101, v101
	v_cvt_pk_bf16_f32 v98, v102, v98
	v_max_f32_e32 v90, v90, v90
	v_cvt_pk_bf16_f32 v99, v99, v100
	v_cvt_pk_bf16_f32 v100, v106, v103
	v_cvt_pk_bf16_f32 v101, v104, v101
	global_store_dwordx4 v[114:115], v[98:101], off offset:256 sc1
	v_max_f32_e32 v90, 0, v90
	v_max_f32_e32 v91, v91, v91
	v_or_b32_e32 v98, 32, v154
	v_max_f32_e32 v92, v92, v92
	v_ashrrev_i32_e32 v99, 31, v98
	v_mul_f32_e32 v100, v90, v90
	v_max_f32_e32 v90, v95, v95
	v_max_f32_e32 v91, 0, v91
	v_max_f32_e32 v92, 0, v92
	v_lshlrev_b64 v[98:99], 15, v[98:99]
	v_max_f32_e32 v94, v94, v94
	v_max_f32_e32 v90, 0, v90
	v_mul_f32_e32 v95, v91, v91
	v_max_f32_e32 v91, v96, v96
	v_mul_f32_e32 v96, v92, v92
	v_max_f32_e32 v92, v97, v97
	v_max_f32_e32 v93, v93, v93
	v_lshl_add_u64 v[98:99], s[86:87], 0, v[98:99]
	v_max_f32_e32 v94, 0, v94
	v_mul_f32_e32 v90, v90, v90
	v_max_f32_e32 v91, 0, v91
	v_max_f32_e32 v92, 0, v92
	v_max_f32_e32 v93, 0, v93
	v_max_f32_e32 v82, v82, v82
	v_lshl_add_u64 v[98:99], v[98:99], 0, v[158:159]
	v_mul_f32_e32 v94, v94, v94
	v_mul_f32_e32 v91, v91, v91
	v_mul_f32_e32 v92, v92, v92
	v_mul_f32_e32 v93, v93, v93
	v_cvt_pk_bf16_f32 v90, v94, v90
	v_max_f32_e32 v82, 0, v82
	v_max_f32_e32 v83, v83, v83
	v_max_f32_e32 v84, v84, v84
	v_cvt_pk_bf16_f32 v91, v91, v92
	v_cvt_pk_bf16_f32 v92, v100, v95
	v_cvt_pk_bf16_f32 v93, v96, v93
	global_store_dwordx4 v[98:99], v[90:93], off sc1
	v_max_f32_e32 v83, 0, v83
	v_max_f32_e32 v84, 0, v84
	v_mul_f32_e32 v90, v82, v82
	v_max_f32_e32 v82, v87, v87
	v_max_f32_e32 v86, v86, v86
	v_max_f32_e32 v82, 0, v82
	v_mul_f32_e32 v87, v83, v83
	v_max_f32_e32 v83, v88, v88
	v_mul_f32_e32 v88, v84, v84
	v_max_f32_e32 v84, v89, v89
	v_max_f32_e32 v85, v85, v85
	v_max_f32_e32 v86, 0, v86
	v_mul_f32_e32 v82, v82, v82
	v_max_f32_e32 v83, 0, v83
	v_max_f32_e32 v84, 0, v84
	v_max_f32_e32 v85, 0, v85
	v_mul_f32_e32 v86, v86, v86
	v_mul_f32_e32 v83, v83, v83
	v_mul_f32_e32 v84, v84, v84
	v_mul_f32_e32 v85, v85, v85
	v_cvt_pk_bf16_f32 v82, v86, v82
	v_max_f32_e32 v74, v74, v74
	v_cvt_pk_bf16_f32 v83, v83, v84
	v_cvt_pk_bf16_f32 v84, v90, v87
	v_cvt_pk_bf16_f32 v85, v88, v85
	global_store_dwordx4 v[98:99], v[82:85], off offset:256 sc1
	v_max_f32_e32 v74, 0, v74
	v_max_f32_e32 v75, v75, v75
	v_or_b32_e32 v82, 48, v154
	v_max_f32_e32 v76, v76, v76
	v_ashrrev_i32_e32 v83, 31, v82
	v_mul_f32_e32 v84, v74, v74
	v_max_f32_e32 v74, v79, v79
	v_max_f32_e32 v75, 0, v75
	v_max_f32_e32 v76, 0, v76
	v_lshlrev_b64 v[82:83], 15, v[82:83]
	v_max_f32_e32 v78, v78, v78
	v_max_f32_e32 v74, 0, v74
	v_mul_f32_e32 v79, v75, v75
	v_max_f32_e32 v75, v80, v80
	v_mul_f32_e32 v80, v76, v76
	v_max_f32_e32 v76, v81, v81
	v_max_f32_e32 v77, v77, v77
	v_lshl_add_u64 v[82:83], s[86:87], 0, v[82:83]
	v_max_f32_e32 v78, 0, v78
	v_mul_f32_e32 v74, v74, v74
	v_max_f32_e32 v75, 0, v75
	v_max_f32_e32 v76, 0, v76
	v_max_f32_e32 v77, 0, v77
	v_max_f32_e32 v66, v66, v66
	v_max_f32_e32 v67, v67, v67
	v_max_f32_e32 v68, v68, v68
	v_lshl_add_u64 v[82:83], v[82:83], 0, v[158:159]
	v_mul_f32_e32 v78, v78, v78
	v_mul_f32_e32 v75, v75, v75
	v_mul_f32_e32 v76, v76, v76
	v_mul_f32_e32 v77, v77, v77
	v_cvt_pk_bf16_f32 v74, v78, v74
	v_max_f32_e32 v66, 0, v66
	v_max_f32_e32 v67, 0, v67
	v_max_f32_e32 v68, 0, v68
	v_cvt_pk_bf16_f32 v75, v75, v76
	v_cvt_pk_bf16_f32 v76, v84, v79
	v_cvt_pk_bf16_f32 v77, v80, v77
	global_store_dwordx4 v[82:83], v[74:77], off sc1
	v_max_f32_e32 v70, v70, v70
	v_max_f32_e32 v69, v69, v69
	v_mul_f32_e32 v74, v66, v66
	v_max_f32_e32 v66, v71, v71
	v_mul_f32_e32 v71, v67, v67
	v_max_f32_e32 v67, v72, v72
	v_mul_f32_e32 v72, v68, v68
	v_max_f32_e32 v68, v73, v73
	v_max_f32_e32 v66, 0, v66
	v_max_f32_e32 v67, 0, v67
	v_max_f32_e32 v68, 0, v68
	v_max_f32_e32 v70, 0, v70
	v_mul_f32_e32 v66, v66, v66
	v_mul_f32_e32 v67, v67, v67
	v_max_f32_e32 v69, 0, v69
	v_mul_f32_e32 v68, v68, v68
	v_max_f32_e32 v58, v58, v58
	v_mul_f32_e32 v70, v70, v70
	v_mul_f32_e32 v69, v69, v69
	v_cvt_pk_bf16_f32 v66, v70, v66
	v_cvt_pk_bf16_f32 v67, v67, v68
	v_cvt_pk_bf16_f32 v68, v74, v71
	v_max_f32_e32 v58, 0, v58
	v_max_f32_e32 v59, v59, v59
	v_max_f32_e32 v60, v60, v60
	v_cvt_pk_bf16_f32 v69, v72, v69
	global_store_dwordx4 v[82:83], v[66:69], off offset:256 sc1
	v_max_f32_e32 v62, v62, v62
	v_max_f32_e32 v59, 0, v59
	v_mul_f32_e32 v68, v58, v58
	v_max_f32_e32 v58, v63, v63
	v_max_f32_e32 v60, 0, v60
	v_max_f32_e32 v62, 0, v62
	v_max_f32_e32 v58, 0, v58
	v_mul_f32_e32 v63, v59, v59
	v_max_f32_e32 v59, v64, v64
	v_mul_f32_e32 v64, v60, v60
	v_max_f32_e32 v60, v65, v65
	v_mul_f32_e32 v62, v62, v62
	v_mul_f32_e32 v58, v58, v58
	v_max_f32_e32 v59, 0, v59
	v_max_f32_e32 v60, 0, v60
	v_max_f32_e32 v61, v61, v61
	v_mul_f32_e32 v59, v59, v59
	v_max_f32_e32 v61, 0, v61
	v_mul_f32_e32 v60, v60, v60
	v_cvt_pk_bf16_f32 v58, v62, v58
	v_add_co_u32_e32 v62, vcc, s59, v146
	v_max_f32_e32 v50, v50, v50
	v_max_f32_e32 v51, v51, v51
	v_max_f32_e32 v52, v52, v52
	v_mul_f32_e32 v61, v61, v61
	v_cvt_pk_bf16_f32 v59, v59, v60
	v_cvt_pk_bf16_f32 v60, v68, v63
	v_addc_co_u32_e32 v63, vcc, 0, v147, vcc
	v_max_f32_e32 v50, 0, v50
	v_max_f32_e32 v51, 0, v51
	v_max_f32_e32 v52, 0, v52
	v_cvt_pk_bf16_f32 v61, v64, v61
	global_store_dwordx4 v[62:63], v[58:61], off sc1
	v_max_f32_e32 v54, v54, v54
	v_max_f32_e32 v53, v53, v53
	v_mul_f32_e32 v58, v50, v50
	v_max_f32_e32 v50, v55, v55
	v_mul_f32_e32 v55, v51, v51
	v_max_f32_e32 v51, v56, v56
	v_mul_f32_e32 v56, v52, v52
	v_max_f32_e32 v52, v57, v57
	v_max_f32_e32 v50, 0, v50
	v_max_f32_e32 v51, 0, v51
	v_max_f32_e32 v52, 0, v52
	v_max_f32_e32 v54, 0, v54
	v_mul_f32_e32 v50, v50, v50
	v_mul_f32_e32 v51, v51, v51
	v_max_f32_e32 v53, 0, v53
	v_mul_f32_e32 v52, v52, v52
	v_max_f32_e32 v42, v42, v42
	v_lshl_add_u64 v[66:67], v[146:147], 0, s[16:17]
	v_mul_f32_e32 v54, v54, v54
	v_mul_f32_e32 v53, v53, v53
	v_cvt_pk_bf16_f32 v50, v54, v50
	v_cvt_pk_bf16_f32 v51, v51, v52
	v_cvt_pk_bf16_f32 v52, v58, v55
	v_max_f32_e32 v42, 0, v42
	v_max_f32_e32 v43, v43, v43
	v_max_f32_e32 v44, v44, v44
	v_cvt_pk_bf16_f32 v53, v56, v53
	global_store_dwordx4 v[66:67], v[50:53], off offset:256 sc1
	v_max_f32_e32 v46, v46, v46
	v_max_f32_e32 v43, 0, v43
	v_mul_f32_e32 v52, v42, v42
	v_max_f32_e32 v42, v47, v47
	v_max_f32_e32 v44, 0, v44
	v_max_f32_e32 v46, 0, v46
	v_max_f32_e32 v42, 0, v42
	v_mul_f32_e32 v47, v43, v43
	v_max_f32_e32 v43, v48, v48
	v_mul_f32_e32 v48, v44, v44
	v_max_f32_e32 v44, v49, v49
	v_mul_f32_e32 v46, v46, v46
	v_mul_f32_e32 v42, v42, v42
	v_max_f32_e32 v43, 0, v43
	v_max_f32_e32 v44, 0, v44
	v_max_f32_e32 v45, v45, v45
	v_mul_f32_e32 v43, v43, v43
	v_max_f32_e32 v45, 0, v45
	v_mul_f32_e32 v44, v44, v44
	v_cvt_pk_bf16_f32 v42, v46, v42
	v_add_co_u32_e32 v46, vcc, s60, v146
	v_max_f32_e32 v34, v34, v34
	v_max_f32_e32 v35, v35, v35
	v_max_f32_e32 v36, v36, v36
	v_mul_f32_e32 v45, v45, v45
	v_cvt_pk_bf16_f32 v43, v43, v44
	v_cvt_pk_bf16_f32 v44, v52, v47
	v_addc_co_u32_e32 v47, vcc, 0, v147, vcc
	v_max_f32_e32 v34, 0, v34
	v_max_f32_e32 v35, 0, v35
	v_max_f32_e32 v36, 0, v36
	v_cvt_pk_bf16_f32 v45, v48, v45
	global_store_dwordx4 v[46:47], v[42:45], off sc1
	v_max_f32_e32 v38, v38, v38
	v_max_f32_e32 v37, v37, v37
	v_mul_f32_e32 v42, v34, v34
	v_max_f32_e32 v34, v39, v39
	v_mul_f32_e32 v39, v35, v35
	v_max_f32_e32 v35, v40, v40
	v_mul_f32_e32 v40, v36, v36
	v_max_f32_e32 v36, v41, v41
	v_max_f32_e32 v34, 0, v34
	v_max_f32_e32 v35, 0, v35
	v_max_f32_e32 v36, 0, v36
	v_max_f32_e32 v38, 0, v38
	v_mul_f32_e32 v34, v34, v34
	v_mul_f32_e32 v35, v35, v35
	v_max_f32_e32 v37, 0, v37
	v_mul_f32_e32 v36, v36, v36
	v_max_f32_e32 v26, v26, v26
	v_lshl_add_u64 v[50:51], v[146:147], 0, s[18:19]
	v_mul_f32_e32 v38, v38, v38
	v_mul_f32_e32 v37, v37, v37
	v_cvt_pk_bf16_f32 v34, v38, v34
	v_cvt_pk_bf16_f32 v35, v35, v36
	v_cvt_pk_bf16_f32 v36, v42, v39
	v_max_f32_e32 v26, 0, v26
	v_max_f32_e32 v27, v27, v27
	v_max_f32_e32 v28, v28, v28
	v_cvt_pk_bf16_f32 v37, v40, v37
	global_store_dwordx4 v[50:51], v[34:37], off offset:256 sc1
	v_max_f32_e32 v30, v30, v30
	v_max_f32_e32 v27, 0, v27
	v_mul_f32_e32 v36, v26, v26
	v_max_f32_e32 v26, v31, v31
	v_max_f32_e32 v28, 0, v28
	v_max_f32_e32 v30, 0, v30
	v_max_f32_e32 v26, 0, v26
	v_mul_f32_e32 v31, v27, v27
	v_max_f32_e32 v27, v32, v32
	v_mul_f32_e32 v32, v28, v28
	v_max_f32_e32 v28, v33, v33
	v_mul_f32_e32 v30, v30, v30
	v_mul_f32_e32 v26, v26, v26
	v_max_f32_e32 v27, 0, v27
	v_max_f32_e32 v28, 0, v28
	v_max_f32_e32 v29, v29, v29
	v_mul_f32_e32 v27, v27, v27
	v_max_f32_e32 v29, 0, v29
	v_mul_f32_e32 v28, v28, v28
	v_cvt_pk_bf16_f32 v26, v30, v26
	v_add_co_u32_e32 v30, vcc, s61, v146
	v_max_f32_e32 v18, v18, v18
	v_max_f32_e32 v19, v19, v19
	v_max_f32_e32 v20, v20, v20
	v_mul_f32_e32 v29, v29, v29
	v_cvt_pk_bf16_f32 v27, v27, v28
	v_cvt_pk_bf16_f32 v28, v36, v31
	v_addc_co_u32_e32 v31, vcc, 0, v147, vcc
	v_max_f32_e32 v18, 0, v18
	v_max_f32_e32 v19, 0, v19
	v_max_f32_e32 v20, 0, v20
	v_cvt_pk_bf16_f32 v29, v32, v29
	global_store_dwordx4 v[30:31], v[26:29], off sc1
	v_max_f32_e32 v22, v22, v22
	v_max_f32_e32 v21, v21, v21
	v_mul_f32_e32 v26, v18, v18
	v_max_f32_e32 v18, v23, v23
	v_mul_f32_e32 v23, v19, v19
	v_max_f32_e32 v19, v24, v24
	v_mul_f32_e32 v24, v20, v20
	v_max_f32_e32 v20, v25, v25
	v_max_f32_e32 v18, 0, v18
	v_max_f32_e32 v19, 0, v19
	v_max_f32_e32 v20, 0, v20
	v_max_f32_e32 v22, 0, v22
	v_mul_f32_e32 v18, v18, v18
	v_mul_f32_e32 v19, v19, v19
	v_max_f32_e32 v21, 0, v21
	v_mul_f32_e32 v20, v20, v20
	v_max_f32_e32 v10, v10, v10
	v_lshl_add_u64 v[34:35], v[146:147], 0, s[20:21]
	v_mul_f32_e32 v22, v22, v22
	v_mul_f32_e32 v21, v21, v21
	v_cvt_pk_bf16_f32 v18, v22, v18
	v_cvt_pk_bf16_f32 v19, v19, v20
	v_cvt_pk_bf16_f32 v20, v26, v23
	v_max_f32_e32 v10, 0, v10
	v_max_f32_e32 v11, v11, v11
	v_max_f32_e32 v12, v12, v12
	v_cvt_pk_bf16_f32 v21, v24, v21
	global_store_dwordx4 v[34:35], v[18:21], off offset:256 sc1
	v_max_f32_e32 v14, v14, v14
	v_max_f32_e32 v11, 0, v11
	v_mul_f32_e32 v20, v10, v10
	v_max_f32_e32 v10, v15, v15
	v_max_f32_e32 v12, 0, v12
	v_max_f32_e32 v14, 0, v14
	v_max_f32_e32 v10, 0, v10
	v_mul_f32_e32 v15, v11, v11
	v_max_f32_e32 v11, v16, v16
	v_mul_f32_e32 v16, v12, v12
	v_max_f32_e32 v12, v17, v17
	v_mul_f32_e32 v14, v14, v14
	v_mul_f32_e32 v10, v10, v10
	v_max_f32_e32 v11, 0, v11
	v_max_f32_e32 v12, 0, v12
	v_max_f32_e32 v13, v13, v13
	v_mul_f32_e32 v11, v11, v11
	v_max_f32_e32 v13, 0, v13
	v_mul_f32_e32 v12, v12, v12
	v_cvt_pk_bf16_f32 v10, v14, v10
	v_add_co_u32_e32 v14, vcc, s62, v146
	v_max_f32_e32 v2, v2, v2
	v_max_f32_e32 v3, v3, v3
	v_max_f32_e32 v4, v4, v4
	v_mul_f32_e32 v13, v13, v13
	v_cvt_pk_bf16_f32 v11, v11, v12
	v_cvt_pk_bf16_f32 v12, v20, v15
	v_addc_co_u32_e32 v15, vcc, 0, v147, vcc
	v_max_f32_e32 v2, 0, v2
	v_max_f32_e32 v3, 0, v3
	v_max_f32_e32 v4, 0, v4
	v_cvt_pk_bf16_f32 v13, v16, v13
	global_store_dwordx4 v[14:15], v[10:13], off sc1
	v_max_f32_e32 v5, v5, v5
	v_max_f32_e32 v6, v6, v6
	v_mul_f32_e32 v10, v2, v2
	v_max_f32_e32 v2, v7, v7
	v_mul_f32_e32 v7, v3, v3
	v_max_f32_e32 v3, v8, v8
	v_mul_f32_e32 v8, v4, v4
	v_max_f32_e32 v4, v9, v9
	v_max_f32_e32 v2, 0, v2
	v_max_f32_e32 v3, 0, v3
	v_max_f32_e32 v4, 0, v4
	v_max_f32_e32 v5, 0, v5
	v_lshl_add_u64 v[18:19], v[146:147], 0, s[28:29]
	v_max_f32_e32 v6, 0, v6
	v_mul_f32_e32 v2, v2, v2
	v_mul_f32_e32 v3, v3, v3
	v_mul_f32_e32 v4, v4, v4
	v_mul_f32_e32 v5, v5, v5
	s_andn2_b64 vcc, exec, s[0:1]
	s_mov_b64 s[0:1], -1
	v_mul_f32_e32 v6, v6, v6
	v_cvt_pk_bf16_f32 v2, v6, v2
	v_cvt_pk_bf16_f32 v3, v3, v4
	v_cvt_pk_bf16_f32 v4, v10, v7
	v_cvt_pk_bf16_f32 v5, v8, v5
	global_store_dwordx4 v[18:19], v[2:5], off offset:256 sc1
	s_cbranch_vccnz .LBB0_803
	s_andn2_b64 vcc, exec, s[4:5]
	s_cbranch_vccnz .LBB0_802
	s_barrier
	s_branch .LBB0_802
